# stick-breaking phase: V tile kept in LDS as d-half blocks and read with transposed 8-byte LDS reads instead of 2-byte reads plus v_perm
# speedup vs baseline: 1.0511x; 1.0041x over previous
.LBB0_390:
	s_or_b64 exec, exec, s[28:29]
	s_mov_b64 s[28:29], -1
	s_and_b64 vcc, exec, s[44:45]
	s_waitcnt lgkmcnt(0)
	s_barrier
	s_cbranch_vccz .LBB0_408
	v_readlane_b32 s26, v254, 53
	v_mov_b32_e32 v0, v240
	v_readlane_b32 s27, v254, 54
	s_andn2_b64 vcc, exec, s[26:27]
	v_readfirstlane_b32 s3, v0
	s_cbranch_vccnz .LBB0_407
	s_ashr_i32 s3, s3, 6
	s_mul_i32 s4, s3, 0x2200
	s_add_i32 s4, s4, 0
	v_and_b32_e32 v1, 63, v0
	v_and_b32_e32 v124, 31, v0
	v_bfe_u32 v6, v0, 5, 1
	v_bfe_u32 v126, v0, 3, 3
	v_and_b32_e32 v2, 7, v0
	v_mov_b32_e32 v0, s4
	s_movk_i32 s20, 0x90
	v_mad_u32_u24 v7, v126, s20, v0
	v_readlane_b32 s20, v254, 55
	s_add_i32 s20, s3, s20
	s_lshl_b32 s20, s20, 5
	s_ashr_i32 s26, s20, 31
	v_readlane_b32 s27, v254, 56
	s_add_u32 s20, s27, s20
	v_readlane_b32 s27, v254, 57
	s_addc_u32 s26, s27, s26
	v_lshlrev_b32_e32 v220, 4, v2
	v_lshl_add_u32 v10, v2, 5, s4
	v_or_b32_e32 v2, s20, v126
	v_mov_b32_e32 v3, s26
	v_lshlrev_b64 v[4:5], 7, v[2:3]
	v_or_b32_e32 v2, s20, v124
	v_lshl_add_u64 v[4:5], s[14:15], 0, v[4:5]
	v_lshlrev_b64 v[2:3], 7, v[2:3]
	v_cmp_gt_u32_e64 s[40:41], 32, v1
	v_lshlrev_b32_e32 v0, 4, v6
	v_mov_b32_e32 v1, v221
	v_lshl_add_u64 v[136:137], v[4:5], 0, v[220:221]
	v_lshl_add_u64 v[4:5], s[12:13], 0, v[2:3]
	v_lshl_add_u64 v[2:3], s[10:11], 0, v[2:3]
	v_lshl_add_u64 v[138:139], v[4:5], 0, v[0:1]
	v_lshl_add_u64 v[4:5], v[2:3], 0, v[0:1]
	v_lshl_add_u64 v[130:131], s[10:11], 0, v[0:1]
	v_lshl_add_u64 v[132:133], s[12:13], 0, v[0:1]
	global_load_dwordx4 v[48:51], v[4:5], off
	global_load_dwordx4 v[52:55], v[4:5], off offset:32
	global_load_dwordx4 v[0:3], v[138:139], off
	global_load_dwordx4 v[16:19], v[138:139], off offset:32
	global_load_dwordx4 v[64:67], v[136:137], off
	global_load_dwordx4 v[68:71], v[136:137], off offset:1024
	global_load_dwordx4 v[56:59], v[4:5], off offset:64
	global_load_dwordx4 v[60:63], v[4:5], off offset:96
	global_load_dwordx4 v[20:23], v[138:139], off offset:64
	global_load_dwordx4 v[24:27], v[138:139], off offset:96
	global_load_dwordx4 v[72:75], v[136:137], off offset:2048
	global_load_dwordx4 v[76:79], v[136:137], off offset:3072
	v_lshlrev_b32_e32 v8, 2, v6
	v_or_b32_e32 v5, 2, v8
	v_cmp_lt_u32_e64 s[46:47], v5, v124
	v_or_b32_e32 v5, 3, v8
	v_cmp_lt_u32_e64 s[48:49], v5, v124
	v_or_b32_e32 v5, 8, v8
	v_cmp_lt_u32_e64 s[50:51], v5, v124
	v_or_b32_e32 v5, 9, v8
	v_cmp_lt_u32_e64 s[52:53], v5, v124
	v_or_b32_e32 v5, 10, v8
	v_or_b32_e32 v4, 1, v8
	v_cmp_lt_u32_e64 s[54:55], v5, v124
	v_or_b32_e32 v5, 11, v8
	v_cmp_lt_u32_e64 s[44:45], v4, v124
	v_cmp_lt_u32_e64 s[56:57], v5, v124
	v_or_b32_e32 v5, 16, v8
	v_mul_u32_u24_e32 v30, 0x90, v4
	v_lshlrev_b32_e32 v32, 2, v124
	v_mul_u32_u24_e32 v4, 0x110, v4
	v_or_b32_e32 v12, 17, v8
	v_add3_u32 v127, s4, v4, v32
	v_mul_u32_u24_e32 v4, 0x110, v5
	v_or_b32_e32 v14, 18, v8
	s_waitcnt vmcnt(15)
	v_add3_u32 v151, s4, v4, v32
	v_mul_u32_u24_e32 v4, 0x110, v12
	v_or_b32_e32 v28, 19, v8
	s_waitcnt vmcnt(14)
	v_add3_u32 v152, s4, v4, v32
	v_mul_u32_u24_e32 v4, 0x110, v14
	v_or_b32_e32 v11, 24, v8
	v_add3_u32 v153, s4, v4, v32
	v_mul_u32_u24_e32 v4, 0x110, v28
	v_or_b32_e32 v13, 25, v8
	v_mul_u32_u24_e32 v29, 0x240, v6
	v_mul_u32_u24_e32 v6, 0x440, v6
	v_add3_u32 v154, s4, v4, v32
	v_mul_u32_u24_e32 v4, 0x110, v11
	v_or_b32_e32 v15, 26, v8
	v_add3_u32 v125, s4, v6, v32
	v_add3_u32 v155, s4, v4, v32
	v_mul_u32_u24_e32 v4, 0x110, v13
	v_and_b32_e32 v6, 64, v245
	v_cmp_lt_u32_e64 s[42:43], v8, v124
	v_or_b32_e32 v8, 27, v8
	v_cmp_lt_u32_e64 s[58:59], v5, v124
	v_mul_u32_u24_e32 v31, 0x90, v5
	s_waitcnt vmcnt(12)
	v_add3_u32 v156, s4, v4, v32
	v_mul_u32_u24_e32 v4, 0x110, v15
	v_xor_b32_e32 v5, 32, v245
	v_add_u32_e32 v6, 64, v6
	v_add3_u32 v157, s4, v4, v32
	v_mul_u32_u24_e32 v4, 0x110, v8
	v_cmp_lt_i32_e32 vcc, v5, v6
	v_lshl_add_u32 v9, v124, 1, s4
	v_add3_u32 v158, s4, v4, v32
	v_mul_u32_u24_e32 v4, 0x110, v126
	v_cndmask_b32_e32 v5, v245, v5, vcc
	v_lshl_add_u64 v[128:129], s[16:17], 0, v[220:221]
	v_lshl_add_u64 v[134:135], s[14:15], 0, v[220:221]
	v_cmp_lt_u32_e64 s[60:61], v11, v124
	v_cmp_lt_u32_e64 s[62:63], v12, v124
	v_cmp_lt_u32_e64 s[64:65], v13, v124
	v_cmp_lt_u32_e64 s[66:67], v14, v124
	v_cmp_lt_u32_e64 s[68:69], v15, v124
	v_cmp_lt_u32_e64 s[70:71], v28, v124
	v_cmp_lt_u32_e64 s[72:73], v8, v124
	v_add_u32_e32 v141, 0x110, v127
	v_add_u32_e32 v143, 0x220, v127
	v_add_u32_e32 v145, 0x770, v127
	v_add_u32_e32 v148, 0x880, v127
	v_add_u32_e32 v149, 0x990, v127
	v_add_u32_e32 v150, 0xaa0, v127
	v_or_b32_e32 v140, 8, v126
	v_or_b32_e32 v142, 16, v126
	v_or_b32_e32 v144, 24, v126
	v_lshlrev_b32_e32 v159, 2, v5
	s_add_i32 s20, s3, 1
	v_add_u32_e32 v160, v10, v4
	v_and_b32_e32 v4, 63, v240
	v_bfe_u32 v5, v4, 2, 1
	v_lshlrev_b32_e32 v5, 11, v5
	v_lshrrev_b32_e32 v6, 3, v4
	v_lshl_add_u32 v5, v6, 6, v5
	v_and_b32_e32 v6, 3, v4
	v_lshl_add_u32 v5, v6, 4, v5
	v_add_u32_e32 v161, s4, v5
	v_lshlrev_b32_e32 v5, 3, v6
	v_bfe_u32 v6, v4, 4, 1
	v_lshl_add_u32 v5, v6, 5, v5
	v_bfe_u32 v6, v4, 2, 2
	v_lshrrev_b32_e32 v4, 5, v4
	v_lshl_add_u32 v6, v4, 2, v6
	v_lshl_add_u32 v5, v6, 6, v5
	v_add_u32_e32 v162, s4, v5
	v_readlane_b32 s26, v254, 2
	s_mov_b32 s27, s88
	s_branch .LBB0_394

.LBB0_394:
	s_lshl_b32 s4, s27, 3
	s_and_b32 s4, s4, 0x78
	s_ashr_i32 s28, s27, 8
	s_add_i32 s4, s4, s3
	s_ashr_i32 s29, s28, 31
	s_lshl_b32 s34, s4, 5
	s_lshl_b32 s35, s27, 10
	s_lshl_b64 s[28:29], s[28:29], 12
	s_and_b32 s35, s35, 0x3c000
	s_ashr_i32 s39, s34, 31
	s_add_u32 s38, s34, s35
	s_addc_u32 s39, s39, 0
	v_mov_b32_e32 v5, s39
	v_or_b32_e32 v4, s38, v126
	v_lshl_add_u64 v[4:5], v[4:5], 0, s[28:29]
	v_lshlrev_b64 v[4:5], 7, v[4:5]
	v_lshl_add_u64 v[6:7], v[128:129], 0, v[4:5]
	v_or_b32_e32 v8, 0x400, v4
	v_mov_b32_e32 v9, v5
	v_lshl_add_u64 v[8:9], v[128:129], 0, v[8:9]
	global_load_dwordx4 v[92:95], v[6:7], off
	global_load_dwordx4 v[88:91], v[8:9], off
	v_or_b32_e32 v6, 0x800, v4
	v_mov_b32_e32 v7, v5
	v_lshl_add_u64 v[6:7], v[128:129], 0, v[6:7]
	v_or_b32_e32 v4, 0xc00, v4
	v_lshl_add_u64 v[4:5], v[128:129], 0, v[4:5]
	global_load_dwordx4 v[84:87], v[6:7], off
	global_load_dwordx4 v[80:83], v[4:5], off
	s_cmp_gt_i32 s4, 0
	s_cselect_b64 vcc, -1, 0
	s_cmp_lt_i32 s4, 1
	s_waitcnt vmcnt(11)
	ds_write_b128 v161, v[64:67]
	s_waitcnt vmcnt(10)
	ds_write_b128 v161, v[68:71] offset:512
	s_waitcnt vmcnt(5)
	ds_write_b128 v161, v[72:75] offset:1024
	s_waitcnt vmcnt(4)
	ds_write_b128 v161, v[76:79] offset:1536
	s_cbranch_scc1 .LBB0_396
	global_load_dwordx4 v[32:35], v[138:139], off offset:-4096
	global_load_dwordx4 v[96:99], v[138:139], off offset:-4064
	global_load_dwordx4 v[64:67], v[136:137], off offset:-4096
	global_load_dwordx4 v[68:71], v[136:137], off offset:-3072
	global_load_dwordx4 v[100:103], v[138:139], off offset:-4032
	global_load_dwordx4 v[104:107], v[138:139], off offset:-4000
	global_load_dwordx4 v[72:75], v[136:137], off offset:-2048
	global_load_dwordx4 v[76:79], v[136:137], off offset:-1024
	v_lshl_add_u64 v[138:139], v[138:139], 0, s[0:1]
	v_lshl_add_u64 v[136:137], v[136:137], 0, s[0:1]
	s_branch .LBB0_397

.LBB0_397:
	v_mfma_f32_32x32x16_bf16 v[0:15], v[0:3], v[48:51], 0
	s_andn2_b64 vcc, exec, vcc
	v_mfma_f32_32x32x16_bf16 v[0:15], v[16:19], v[52:55], v[0:15]
	v_mfma_f32_32x32x16_bf16 v[0:15], v[20:23], v[56:59], v[0:15]
	v_mfma_f32_32x32x16_bf16 v[0:15], v[24:27], v[60:63], v[0:15]
	s_nop 11
	v_mul_f32_e32 v0, 0xbfb8aa3b, v0
	v_exp_f32_e32 v0, v0
	s_nop 0
	v_add_f32_e32 v0, 1.0, v0
	v_rcp_f32_e32 v0, v0
	s_nop 0
	v_cndmask_b32_e64 v16, 0, v0, s[42:43]
	v_sub_f32_e32 v0, 1.0, v0
	v_cndmask_b32_e64 v18, 1.0, v0, s[42:43]
	v_mul_f32_e32 v0, 0xbfb8aa3b, v1
	v_exp_f32_e32 v0, v0
	s_nop 0
	v_add_f32_e32 v0, 1.0, v0
	v_rcp_f32_e32 v0, v0
	s_nop 0
	v_cndmask_b32_e64 v17, 0, v0, s[44:45]
	v_sub_f32_e32 v1, 1.0, v0
	v_mul_f32_e32 v0, 0xbfb8aa3b, v2
	v_mul_f32_e32 v2, 0xbfb8aa3b, v3
	v_mul_f32_e32 v3, 0xbfb8aa3b, v4
	v_mul_f32_e32 v4, 0xbfb8aa3b, v5
	v_exp_f32_e32 v4, v4
	v_exp_f32_e32 v3, v3
	v_exp_f32_e32 v0, v0
	v_exp_f32_e32 v2, v2
	v_add_f32_e32 v4, 1.0, v4
	v_rcp_f32_e32 v4, v4
	v_add_f32_e32 v3, 1.0, v3
	v_rcp_f32_e32 v3, v3
	v_add_f32_e32 v0, 1.0, v0
	v_cndmask_b32_e64 v28, 0, v4, s[52:53]
	v_sub_f32_e32 v22, 1.0, v4
	v_mul_f32_e32 v4, 0xbfb8aa3b, v6
	v_exp_f32_e32 v4, v4
	v_mul_f32_e32 v6, 0xbfb8aa3b, v13
	v_exp_f32_e32 v6, v6
	v_cndmask_b32_e64 v21, 0, v3, s[50:51]
	v_add_f32_e32 v4, 1.0, v4
	v_rcp_f32_e32 v4, v4
	v_add_f32_e32 v6, 1.0, v6
	v_rcp_f32_e32 v6, v6
	v_sub_f32_e32 v3, 1.0, v3
	v_cndmask_b32_e64 v29, 0, v4, s[54:55]
	v_sub_f32_e32 v4, 1.0, v4
	v_cndmask_b32_e64 v23, 1.0, v4, s[54:55]
	v_mul_f32_e32 v4, 0xbfb8aa3b, v7
	v_exp_f32_e32 v4, v4
	v_cndmask_b32_e64 v45, 0, v6, s[64:65]
	v_cndmask_b32_e64 v3, 1.0, v3, s[50:51]
	v_add_f32_e32 v2, 1.0, v2
	v_add_f32_e32 v4, 1.0, v4
	v_rcp_f32_e32 v4, v4
	v_rcp_f32_e32 v0, v0
	v_rcp_f32_e32 v2, v2
	v_cndmask_b32_e64 v30, 0, v4, s[56:57]
	v_sub_f32_e32 v4, 1.0, v4
	v_cndmask_b32_e64 v31, 1.0, v4, s[56:57]
	v_mul_f32_e32 v4, 0xbfb8aa3b, v8
	v_exp_f32_e32 v4, v4
	v_mul_f32_e32 v8, 0xbfb8aa3b, v14
	v_exp_f32_e32 v8, v8
	v_cndmask_b32_e64 v14, 1.0, v22, s[52:53]
	v_add_f32_e32 v4, 1.0, v4
	v_rcp_f32_e32 v5, v4
	v_mul_f32_e32 v4, 0xbfb8aa3b, v9
	v_exp_f32_e32 v4, v4
	v_add_f32_e32 v8, 1.0, v8
	v_rcp_f32_e32 v8, v8
	v_cndmask_b32_e64 v36, 0, v5, s[58:59]
	v_add_f32_e32 v4, 1.0, v4
	v_rcp_f32_e32 v7, v4
	v_mul_f32_e32 v4, 0xbfb8aa3b, v10
	v_exp_f32_e32 v4, v4
	v_mul_f32_e32 v10, 0xbfb8aa3b, v15
	v_exp_f32_e32 v10, v10
	v_cndmask_b32_e64 v37, 0, v7, s[62:63]
	v_add_f32_e32 v4, 1.0, v4
	v_rcp_f32_e32 v9, v4
	v_mul_f32_e32 v4, 0xbfb8aa3b, v11
	v_exp_f32_e32 v4, v4
	v_add_f32_e32 v10, 1.0, v10
	v_rcp_f32_e32 v10, v10
	v_cndmask_b32_e64 v38, 0, v9, s[66:67]
	v_add_f32_e32 v4, 1.0, v4
	v_rcp_f32_e32 v11, v4
	v_mul_f32_e32 v4, 0xbfb8aa3b, v12
	v_exp_f32_e32 v4, v4
	v_pk_add_f32 v[6:7], v[6:7], 1.0 op_sel_hi:[1,0] neg_lo:[1,0] neg_hi:[1,0]
	v_cndmask_b32_e64 v39, 0, v11, s[70:71]
	v_cndmask_b32_e64 v46, 0, v8, s[68:69]
	v_add_f32_e32 v4, 1.0, v4
	v_rcp_f32_e32 v4, v4
	v_pk_add_f32 v[8:9], v[8:9], 1.0 op_sel_hi:[1,0] neg_lo:[1,0] neg_hi:[1,0]
	v_cndmask_b32_e64 v47, 0, v10, s[72:73]
	v_pk_add_f32 v[10:11], v[10:11], 1.0 op_sel_hi:[1,0] neg_lo:[1,0] neg_hi:[1,0]
	v_cndmask_b32_e64 v44, 0, v4, s[60:61]
	v_pk_add_f32 v[4:5], v[4:5], 1.0 op_sel_hi:[1,0] neg_lo:[1,0] neg_hi:[1,0]
	v_cndmask_b32_e64 v9, 1.0, v9, s[66:67]
	v_cndmask_b32_e64 v5, 1.0, v5, s[58:59]
	v_cndmask_b32_e64 v4, 1.0, v4, s[60:61]
	v_cndmask_b32_e64 v8, 1.0, v8, s[68:69]
	v_cndmask_b32_e64 v11, 1.0, v11, s[70:71]
	v_cndmask_b32_e64 v10, 1.0, v10, s[72:73]
	v_cndmask_b32_e64 v7, 1.0, v7, s[62:63]
	v_cndmask_b32_e64 v6, 1.0, v6, s[64:65]
	v_pk_mul_f32 v[4:5], v[4:5], v[6:7]
	v_pk_mul_f32 v[8:9], v[8:9], v[10:11]
	v_mul_f32_e32 v3, v3, v14
	v_pk_mul_f32 v[4:5], v[4:5], v[8:9]
	ds_bpermute_b32 v12, v159, v4
	ds_bpermute_b32 v13, v159, v5
	v_mul_f32_e32 v22, v23, v31
	v_mul_f32_e32 v24, v3, v22
	ds_bpermute_b32 v26, v159, v24
	v_cndmask_b32_e64 v19, 0, v0, s[46:47]
	s_waitcnt lgkmcnt(1)
	v_pk_mul_f32 v[4:5], v[4:5], v[12:13]
	v_sub_f32_e32 v0, 1.0, v0
	v_mov_b32_e32 v25, v4
	v_mov_b32_e32 v27, v5
	v_cndmask_b32_e64 v20, 0, v2, s[48:49]
	v_sub_f32_e32 v2, 1.0, v2
	s_waitcnt lgkmcnt(0)
	v_pk_mul_f32 v[24:25], v[24:25], v[26:27]
	v_cndmask_b32_e64 v0, 1.0, v0, s[46:47]
	v_cndmask_b32_e64 v2, 1.0, v2, s[48:49]
	v_cndmask_b32_e64 v15, 1.0, v26, s[40:41]
	v_cndmask_b32_e64 v26, 1.0, v1, s[44:45]
	v_mov_b32_e32 v1, v24
	v_mov_b32_e32 v3, v25
	v_mul_f32_e32 v18, v18, v26
	v_pk_mul_f32 v[40:41], v[0:1], v[2:3]
	v_mov_b32_e32 v23, v25
	v_mul_f32_e32 v42, v18, v40
	ds_bpermute_b32 v43, v159, v42
	s_waitcnt lgkmcnt(0)
	v_cndmask_b32_e64 v27, 1.0, v43, s[40:41]
	v_pk_mul_f32 v[0:1], v[26:27], v[40:41]
	s_nop 0
	v_mul_f32_e32 v0, v0, v1
	v_mul_f32_e32 v16, v16, v0
	v_mul_f32_e32 v0, v40, v1
	v_mul_f32_e32 v17, v17, v0
	v_mul_f32_e32 v0, v2, v1
	v_mul_f32_e32 v18, v19, v0
	v_mul_f32_e32 v19, v20, v1
	v_pk_mul_f32 v[0:1], v[14:15], v[22:23]
	v_pk_mov_b32 v[2:3], v[8:9], v[4:5] op_sel:[1,0]
	v_mul_f32_e32 v0, v0, v1
	v_mul_f32_e32 v14, v21, v0
	v_mul_f32_e32 v0, v22, v1
	v_mul_f32_e32 v15, v28, v0
	v_mul_f32_e32 v0, v31, v1
	v_mul_f32_e32 v20, v29, v0
	v_mul_f32_e32 v21, v30, v1
	v_cndmask_b32_e64 v1, 1.0, v13, s[40:41]
	v_mov_b32_e32 v0, v7
	v_pk_mul_f32 v[0:1], v[0:1], v[2:3]
	v_cndmask_b32_e64 v4, 1.0, v12, s[40:41]
	v_mul_f32_e32 v5, v6, v8
	v_mul_f32_e32 v0, v0, v1
	v_mul_f32_e32 v2, v9, v1
	v_mul_f32_e32 v3, v11, v1
	v_mul_f32_e32 v5, v4, v5
	v_mul_f32_e32 v6, v4, v8
	v_mul_f32_e32 v7, v4, v10
	v_mul_f32_e32 v0, v36, v0
	v_mul_f32_e32 v2, v37, v2
	v_mul_f32_e32 v3, v38, v3
	v_mul_f32_e32 v1, v39, v1
	v_mul_f32_e32 v5, v44, v5
	v_mul_f32_e32 v6, v45, v6
	v_mul_f32_e32 v7, v46, v7
	v_mul_f32_e32 v4, v4, v47
	v_cvt_pk_bf16_f32 v16, v16, v17
	v_cvt_pk_bf16_f32 v17, v18, v19
	v_cvt_pk_bf16_f32 v18, v14, v15
	v_cvt_pk_bf16_f32 v19, v20, v21
	v_cvt_pk_bf16_f32 v36, v0, v2
	v_cvt_pk_bf16_f32 v37, v3, v1
	v_cvt_pk_bf16_f32 v38, v5, v6
	v_cvt_pk_bf16_f32 v39, v7, v4
	ds_read_b64_tr_b16 v[0:1], v162
	ds_read_b64_tr_b16 v[2:3], v162 offset:512
	ds_read_b64_tr_b16 v[20:21], v162 offset:2048
	ds_read_b64_tr_b16 v[22:23], v162 offset:2560
	ds_read_b64_tr_b16 v[44:45], v162 offset:1024
	ds_read_b64_tr_b16 v[46:47], v162 offset:1536
	s_waitcnt lgkmcnt(4)
	v_mfma_f32_32x32x16_bf16 v[0:15], v[16:19], v[0:3], 0
	s_waitcnt lgkmcnt(2)
	v_mfma_f32_32x32x16_bf16 v[16:31], v[16:19], v[20:23], 0
	s_waitcnt lgkmcnt(0)
	v_mfma_f32_32x32x16_bf16 v[0:15], v[36:39], v[44:47], v[0:15]
	ds_read_b64_tr_b16 v[44:45], v162 offset:3072
	ds_read_b64_tr_b16 v[46:47], v162 offset:3584
	s_waitcnt lgkmcnt(0)
	v_mfma_f32_32x32x16_bf16 v[16:31], v[36:39], v[44:47], v[16:31]
	s_cbranch_vccnz .LBB0_405
	s_and_b32 s4, s26, 0x78
	v_mul_f32_e32 v36, v42, v43
	s_add_i32 s80, s20, s4
	v_mul_f32_e32 v146, v36, v41
	s_branch .LBB0_400

.LBB0_400:
	v_cmp_eq_f32_e32 vcc, 0, v146
	s_cmp_eq_u64 vcc, exec
	s_mov_b64 s[34:35], -1
	s_cbranch_scc1 .LBB0_399
	s_cmp_eq_u32 s80, 2
	s_waitcnt vmcnt(5)
	ds_write_b128 v161, v[64:67]
	s_waitcnt vmcnt(4)
	ds_write_b128 v161, v[68:71] offset:512
	s_waitcnt vmcnt(1)
	ds_write_b128 v161, v[72:75] offset:1024
	s_waitcnt vmcnt(0)
	ds_write_b128 v161, v[76:79] offset:1536
	s_cbranch_scc1 .LBB0_403
	global_load_dwordx4 v[108:111], v[138:139], off offset:-4096
	global_load_dwordx4 v[112:115], v[138:139], off offset:-4064
	global_load_dwordx4 v[64:67], v[136:137], off offset:-4096
	global_load_dwordx4 v[68:71], v[136:137], off offset:-3072
	global_load_dwordx4 v[116:119], v[138:139], off offset:-4032
	global_load_dwordx4 v[120:123], v[138:139], off offset:-4000
	global_load_dwordx4 v[72:75], v[136:137], off offset:-2048
	global_load_dwordx4 v[76:79], v[136:137], off offset:-1024
	v_lshl_add_u64 v[138:139], v[138:139], 0, s[0:1]
	v_lshl_add_u64 v[136:137], v[136:137], 0, s[0:1]
	s_branch .LBB0_404

.LBB0_404:
	v_mfma_f32_32x32x16_bf16 v[32:47], v[32:35], v[48:51], 0
	s_add_i32 s80, s80, -1
	s_cmp_lt_u32 s80, 2
	s_cselect_b64 s[34:35], -1, 0
	v_mfma_f32_32x32x16_bf16 v[32:47], v[96:99], v[52:55], v[32:47]
	v_mfma_f32_32x32x16_bf16 v[32:47], v[100:103], v[56:59], v[32:47]
	v_mfma_f32_32x32x16_bf16 v[32:47], v[104:107], v[60:63], v[32:47]
	s_nop 11
	v_mul_f32_e32 v33, 0xbfb8aa3b, v33
	v_mul_f32_e32 v34, 0xbfb8aa3b, v34
	v_exp_f32_e32 v33, v33
	v_exp_f32_e32 v34, v34
	v_mul_f32_e32 v41, 0xbfb8aa3b, v41
	v_exp_f32_e32 v41, v41
	v_add_f32_e32 v33, 1.0, v33
	v_add_f32_e32 v96, 1.0, v34
	v_mul_f32_e32 v42, 0xbfb8aa3b, v42
	v_rcp_f32_e32 v34, v33
	v_rcp_f32_e32 v33, v96
	v_exp_f32_e32 v96, v42
	v_add_f32_e32 v41, 1.0, v41
	v_mul_f32_e32 v42, 0xbfb8aa3b, v43
	v_mul_f32_e32 v45, 0xbfb8aa3b, v45
	v_mul_f32_e32 v46, 0xbfb8aa3b, v46
	v_mul_f32_e32 v40, 0xbfb8aa3b, v40
	v_exp_f32_e32 v43, v42
	v_rcp_f32_e32 v42, v41
	v_add_f32_e32 v41, 1.0, v96
	v_mul_f32_e32 v44, 0xbfb8aa3b, v44
	v_exp_f32_e32 v45, v45
	v_exp_f32_e32 v96, v46
	v_mul_f32_e32 v46, 0xbfb8aa3b, v47
	v_exp_f32_e32 v40, v40
	v_exp_f32_e32 v44, v44
	v_exp_f32_e32 v47, v46
	v_add_f32_e32 v45, 1.0, v45
	v_add_f32_e32 v40, 1.0, v40
	v_add_f32_e32 v43, 1.0, v43
	v_add_f32_e32 v44, 1.0, v44
	v_rcp_f32_e32 v46, v45
	v_add_f32_e32 v45, 1.0, v96
	v_add_f32_e32 v47, 1.0, v47
	v_rcp_f32_e32 v40, v40
	v_rcp_f32_e32 v41, v41
	v_rcp_f32_e32 v43, v43
	v_rcp_f32_e32 v44, v44
	v_rcp_f32_e32 v45, v45
	v_rcp_f32_e32 v47, v47
	v_mul_f32_e32 v36, 0xbfb8aa3b, v36
	v_mul_f32_e32 v37, 0xbfb8aa3b, v37
	v_mul_f32_e32 v38, 0xbfb8aa3b, v38
	v_mul_f32_e32 v39, 0xbfb8aa3b, v39
	v_exp_f32_e32 v36, v36
	v_exp_f32_e32 v37, v37
	v_exp_f32_e32 v38, v38
	v_exp_f32_e32 v39, v39
	v_pk_add_f32 v[98:99], v[40:41], 1.0 op_sel_hi:[1,0] neg_lo:[1,0] neg_hi:[1,0]
	v_pk_add_f32 v[100:101], v[42:43], 1.0 op_sel_hi:[1,0] neg_lo:[1,0] neg_hi:[1,0]
	v_pk_add_f32 v[102:103], v[44:45], 1.0 op_sel_hi:[1,0] neg_lo:[1,0] neg_hi:[1,0]
	v_pk_add_f32 v[104:105], v[46:47], 1.0 op_sel_hi:[1,0] neg_lo:[1,0] neg_hi:[1,0]
	v_pk_mul_f32 v[98:99], v[98:99], v[100:101]
	v_pk_mul_f32 v[102:103], v[102:103], v[104:105]
	v_mov_b32_e32 v107, v98
	v_mov_b32_e32 v106, v102
	v_mov_b32_e32 v98, v103
	v_add_f32_e32 v36, 1.0, v36
	v_add_f32_e32 v37, 1.0, v37
	v_add_f32_e32 v97, 1.0, v38
	v_add_f32_e32 v39, 1.0, v39
	v_pk_mul_f32 v[106:107], v[106:107], v[98:99]
	v_mul_f32_e32 v32, 0xbfb8aa3b, v32
	v_mul_f32_e32 v35, 0xbfb8aa3b, v35
	v_rcp_f32_e32 v36, v36
	v_rcp_f32_e32 v38, v37
	v_rcp_f32_e32 v37, v97
	v_rcp_f32_e32 v39, v39
	ds_bpermute_b32 v167, v159, v107
	ds_bpermute_b32 v166, v159, v106
	v_exp_f32_e32 v32, v32
	v_exp_f32_e32 v35, v35
	v_pk_add_f32 v[170:171], v[36:37], 1.0 op_sel_hi:[1,0] neg_lo:[1,0] neg_hi:[1,0]
	v_pk_add_f32 v[172:173], v[38:39], 1.0 op_sel_hi:[1,0] neg_lo:[1,0] neg_hi:[1,0]
	v_add_f32_e32 v32, 1.0, v32
	v_add_f32_e32 v35, 1.0, v35
	v_pk_mul_f32 v[170:171], v[170:171], v[172:173]
	s_waitcnt lgkmcnt(0)
	v_pk_mul_f32 v[106:107], v[106:107], v[166:167]
	v_rcp_f32_e32 v32, v32
	v_rcp_f32_e32 v35, v35
	v_mov_b32_e32 v174, v170
	v_mov_b32_e32 v175, v106
	v_mov_b32_e32 v176, v171
	v_mov_b32_e32 v177, v107
	v_pk_mul_f32 v[174:175], v[174:175], v[176:177]
	ds_bpermute_b32 v177, v159, v174
	v_pk_add_f32 v[96:97], v[32:33], 1.0 op_sel_hi:[1,0] neg_lo:[1,0] neg_hi:[1,0]
	v_pk_add_f32 v[168:169], v[34:35], 1.0 op_sel_hi:[1,0] neg_lo:[1,0] neg_hi:[1,0]
	v_mov_b32_e32 v179, v174
	v_pk_mul_f32 v[96:97], v[96:97], v[168:169]
	v_mov_b32_e32 v182, v168
	v_mov_b32_e32 v178, v96
	v_mov_b32_e32 v176, v97
	s_waitcnt lgkmcnt(0)
	v_pk_mul_f32 v[178:179], v[178:179], v[176:177]
	ds_bpermute_b32 v174, v159, v178
	v_mov_b32_e32 v180, v97
	v_cndmask_b32_e64 v102, 1.0, v166, s[40:41]
	v_mov_b32_e32 v147, v104
	s_waitcnt lgkmcnt(0)
	v_pk_mul_f32 v[178:179], v[178:179], v[174:175]
	s_nop 0
	v_mul_f32_e32 v181, v146, v179
	v_cndmask_b32_e64 v183, 1.0, v174, s[40:41]
	v_pk_mul_f32 v[180:181], v[182:183], v[180:181]
	s_nop 0
	v_mul_f32_e32 v96, v180, v181
	v_mul_f32_e32 v96, v32, v96
	v_mul_f32_e32 v32, v97, v181
	v_mul_f32_e32 v97, v34, v32
	v_mul_f32_e32 v32, v169, v181
	v_mul_f32_e32 v98, v33, v32
	v_mul_f32_e32 v107, v35, v181
	v_mul_f32_e32 v33, v146, v175
	v_cndmask_b32_e64 v35, 1.0, v177, s[40:41]
	v_mov_b32_e32 v34, v172
	v_mov_b32_e32 v32, v171
	v_pk_mul_f32 v[32:33], v[34:35], v[32:33]
	v_cndmask_b32_e64 v35, 1.0, v167, s[40:41]
	v_mul_f32_e32 v32, v32, v33
	v_mul_f32_e32 v36, v36, v32
	v_mul_f32_e32 v32, v171, v33
	v_mul_f32_e32 v38, v38, v32
	v_mul_f32_e32 v32, v173, v33
	v_mul_f32_e32 v37, v37, v32
	v_mul_f32_e32 v39, v39, v33
	v_mul_f32_e32 v33, v146, v106
	v_mov_b32_e32 v34, v100
	v_mov_b32_e32 v32, v99
	v_pk_mul_f32 v[32:33], v[34:35], v[32:33]
	s_nop 0
	v_mul_f32_e32 v32, v32, v33
	v_mul_f32_e32 v40, v40, v32
	v_mul_f32_e32 v32, v99, v33
	v_mul_f32_e32 v42, v42, v32
	v_mul_f32_e32 v32, v101, v33
	v_mul_f32_e32 v41, v41, v32
	v_mul_f32_e32 v43, v43, v33
	v_pk_mul_f32 v[32:33], v[146:147], v[102:103]
	s_nop 0
	v_mul_f32_e32 v33, v32, v33
	v_mul_f32_e32 v44, v44, v33
	v_mul_f32_e32 v33, v32, v103
	v_mul_f32_e32 v46, v46, v33
	v_mul_f32_e32 v33, v32, v105
	v_mul_f32_e32 v45, v45, v33
	v_mul_f32_e32 v47, v47, v32
	v_cvt_pk_bf16_f32 v32, v96, v97
	v_cvt_pk_bf16_f32 v33, v98, v107
	v_cvt_pk_bf16_f32 v34, v36, v38
	v_cvt_pk_bf16_f32 v35, v37, v39
	v_cvt_pk_bf16_f32 v36, v40, v42
	v_cvt_pk_bf16_f32 v37, v41, v43
	v_cvt_pk_bf16_f32 v38, v44, v46
	v_cvt_pk_bf16_f32 v39, v45, v47
	ds_read_b64_tr_b16 v[40:41], v162
	ds_read_b64_tr_b16 v[42:43], v162 offset:512
	ds_read_b64_tr_b16 v[44:45], v162 offset:2048
	ds_read_b64_tr_b16 v[46:47], v162 offset:2560
	ds_read_b64_tr_b16 v[96:97], v162 offset:1024
	ds_read_b64_tr_b16 v[98:99], v162 offset:1536
	ds_read_b64_tr_b16 v[100:101], v162 offset:3072
	ds_read_b64_tr_b16 v[102:103], v162 offset:3584
	s_waitcnt lgkmcnt(6)
	v_mfma_f32_32x32x16_bf16 v[0:15], v[32:35], v[40:43], v[0:15]
	s_waitcnt lgkmcnt(4)
	v_mfma_f32_32x32x16_bf16 v[16:31], v[32:35], v[44:47], v[16:31]
	s_waitcnt lgkmcnt(2)
	v_mfma_f32_32x32x16_bf16 v[0:15], v[36:39], v[96:99], v[0:15]
	s_waitcnt lgkmcnt(0)
	v_mfma_f32_32x32x16_bf16 v[16:31], v[36:39], v[100:103], v[16:31]
	s_waitcnt vmcnt(2)
	v_mov_b64_e32 v[104:105], v[120:121]
	v_mov_b64_e32 v[100:101], v[116:117]
	v_mov_b64_e32 v[96:97], v[112:113]
	v_mul_f32_e32 v32, v178, v179
	v_mul_f32_e32 v146, v146, v32
	v_mov_b64_e32 v[32:33], v[108:109]
	v_mov_b64_e32 v[106:107], v[122:123]
	v_mov_b64_e32 v[102:103], v[118:119]
	v_mov_b64_e32 v[98:99], v[114:115]
	v_mov_b64_e32 v[34:35], v[110:111]
	s_and_b64 vcc, exec, s[34:35]
	s_cbranch_vccz .LBB0_400
